# v29 + prep-phase row loop: gain vector loaded once per wave, the step's modulation vectors requested together, next step's x rows loaded while this step is reduced and stored
# speedup vs baseline: 1.0021x; 1.0021x over previous
; __device__ __forceinline__ unsigned pk2(float lo, float hi) { unsigned r; asm volatile("v_cvt_pk_bf16_f32 %0, %1, %2" : "=v"(r) : "v"(lo), "v"(hi)); return r; }
; __device__ __forceinline__ void prep_phase(const PL& P, int gw, int NGW, int lane) {
;     ...
;       for (int row0 = gw; row0 < M; row0 += 2 * NGW) {
;           f32x4 v[2][4]; float ss[2];
; #pragma unroll
;           for (int k = 0; k < 2; ++k) { const int row = row0 + k * NGW; const f32x4* xr = (const f32x4*)(x + (size_t)row * D) + lane;
; #pragma unroll
;               for (int j = 0; j < 4; ++j) v[k][j] = xr[64 * j]; }
; #pragma unroll
;           for (int k = 0; k < 2; ++k) { ss[k] = 0.f;
; #pragma unroll
;               for (int j = 0; j < 4; ++j) ss[k] += (v[k][j].x * v[k][j].x + v[k][j].y * v[k][j].y) + (v[k][j].z * v[k][j].z + v[k][j].w * v[k][j].w); }
;           ss[0] = xadd<1>(ss[0]); ss[1] = xadd<1>(ss[1]); ss[0] = xadd<2>(ss[0]); ss[1] = xadd<2>(ss[1]); ss[0] = xadd<4>(ss[0]); ss[1] = xadd<4>(ss[1]);
;           ss[0] = xadd<8>(ss[0]); ss[1] = xadd<8>(ss[1]); ss[0] = xadd<16>(ss[0]); ss[1] = xadd<16>(ss[1]); ss[0] = xadd<32>(ss[0]); ss[1] = xadd<32>(ss[1]);
; #pragma unroll
;           for (int k = 0; k < 2; ++k) { const int row = row0 + k * NGW; const int b = row >> 13; if (lane == 0) ssq0[row] = ss[k];
;               v2u* ao = (v2u*)(a + (size_t)row * D) + lane;
; #pragma unroll
;               for (int j = 0; j < 4; ++j) { const f32x4 gg = *((const f32x4*)g + lane + 64 * j), c4 = *((const f32x4*)(sc + (size_t)b * NMOD) + lane + 64 * j);
;                   const f32x4 y = v[k][j] * gg * (c4 + 1.0f); v2u w; w.x = pk2(y.x, y.y); w.y = pk2(y.z, y.w); ao[64 * j] = w; } } } }
.LBB0_572:
.LBB0_573:
	global_load_dwordx4 v[56:59], v[36:37], off
	global_load_dwordx4 v[60:63], v[36:37], off offset:1024
	global_load_dwordx4 v[64:67], v[36:37], off offset:2048
	global_load_dwordx4 v[68:71], v[36:37], off offset:3072
	s_ashr_i32 s13, s10, 31
	s_mov_b32 s12, s10
	s_lshl_b64 s[12:13], s[12:13], 12
	v_lshl_add_u64 v[136:137], v[32:33], 0, s[12:13]
	global_load_dwordx4 v[100:103], v[136:137], off
	global_load_dwordx4 v[96:99], v[136:137], off offset:1024
	global_load_dwordx4 v[92:95], v[136:137], off offset:2048
	global_load_dwordx4 v[88:91], v[136:137], off offset:3072
	s_add_i32 s14, s10, s2
	s_ashr_i32 s15, s14, 31
	s_lshl_b64 s[14:15], s[14:15], 12
	v_lshl_add_u64 v[136:137], v[32:33], 0, s[14:15]
	global_load_dwordx4 v[84:87], v[136:137], off
	global_load_dwordx4 v[80:83], v[136:137], off offset:1024
	global_load_dwordx4 v[76:79], v[136:137], off offset:2048
	global_load_dwordx4 v[72:75], v[136:137], off offset:3072
	s_ashr_i32 s12, s10, 13
	v_mad_i64_i32 v[138:139], s[12:13], s12, v226, v[38:39]
	global_load_dwordx4 v[104:107], v[138:139], off
	global_load_dwordx4 v[108:111], v[138:139], off offset:1024
	global_load_dwordx4 v[112:115], v[138:139], off offset:2048
	global_load_dwordx4 v[116:119], v[138:139], off offset:3072
	s_add_i32 s12, s10, s2
	s_ashr_i32 s12, s12, 13
	v_mad_i64_i32 v[138:139], s[12:13], s12, v226, v[38:39]
	global_load_dwordx4 v[120:123], v[138:139], off
	global_load_dwordx4 v[124:127], v[138:139], off offset:1024
	global_load_dwordx4 v[128:131], v[138:139], off offset:2048
	global_load_dwordx4 v[132:135], v[138:139], off offset:3072
	s_waitcnt vmcnt(8)
.Lprep_loop:
	v_mov_b64_e32 v[0:1], v[72:73]
	v_mov_b64_e32 v[2:3], v[74:75]
	v_mov_b64_e32 v[4:5], v[76:77]
	v_mov_b64_e32 v[6:7], v[78:79]
	v_mov_b64_e32 v[8:9], v[80:81]
	v_mov_b64_e32 v[10:11], v[82:83]
	v_mov_b64_e32 v[12:13], v[84:85]
	v_mov_b64_e32 v[14:15], v[86:87]
	v_mov_b64_e32 v[16:17], v[88:89]
	v_mov_b64_e32 v[18:19], v[90:91]
	v_mov_b64_e32 v[20:21], v[92:93]
	v_mov_b64_e32 v[22:23], v[94:95]
	v_mov_b64_e32 v[24:25], v[96:97]
	v_mov_b64_e32 v[26:27], v[98:99]
	v_mov_b64_e32 v[28:29], v[100:101]
	v_mov_b64_e32 v[30:31], v[102:103]
	s_add_i32 s0, s10, s2
	s_add_i32 s1, s0, s2
	s_cmpk_gt_i32 s1, 0x7fff
	s_cbranch_scc1 .Lprep_nonext1
	s_ashr_i32 s13, s1, 31
	s_mov_b32 s12, s1
	s_lshl_b64 s[12:13], s[12:13], 12
	v_lshl_add_u64 v[136:137], v[32:33], 0, s[12:13]
	global_load_dwordx4 v[100:103], v[136:137], off
	global_load_dwordx4 v[96:99], v[136:137], off offset:1024
	global_load_dwordx4 v[92:95], v[136:137], off offset:2048
	global_load_dwordx4 v[88:91], v[136:137], off offset:3072
	s_add_i32 s14, s1, s2
	s_ashr_i32 s15, s14, 31
	s_lshl_b64 s[14:15], s[14:15], 12
	v_lshl_add_u64 v[136:137], v[32:33], 0, s[14:15]
	global_load_dwordx4 v[84:87], v[136:137], off
	global_load_dwordx4 v[80:83], v[136:137], off offset:1024
	global_load_dwordx4 v[76:79], v[136:137], off offset:2048
	global_load_dwordx4 v[72:75], v[136:137], off offset:3072
.Lprep_nonext1:
	v_mul_f32_e32 v40, v29, v29
	v_mul_f32_e32 v41, v31, v31
	v_mul_f32_e32 v42, v25, v25
	v_mul_f32_e32 v43, v27, v27
	v_mul_f32_e32 v44, v21, v21
	v_mul_f32_e32 v45, v23, v23
	v_fmac_f32_e32 v40, v28, v28
	v_fmac_f32_e32 v41, v30, v30
	v_fmac_f32_e32 v42, v24, v24
	v_fmac_f32_e32 v43, v26, v26
	v_mul_f32_e32 v48, v13, v13
	v_mul_f32_e32 v49, v15, v15
	v_mul_f32_e32 v50, v9, v9
	v_mul_f32_e32 v51, v11, v11
	v_fmac_f32_e32 v44, v20, v20
	v_fmac_f32_e32 v45, v22, v22
	v_mul_f32_e32 v52, v5, v5
	v_mul_f32_e32 v53, v7, v7
	v_add_f32_e32 v40, v40, v41
	v_add_f32_e32 v41, v42, v43
	v_fmac_f32_e32 v48, v12, v12
	v_fmac_f32_e32 v49, v14, v14
	v_fmac_f32_e32 v50, v8, v8
	v_fmac_f32_e32 v51, v10, v10
	v_mul_f32_e32 v46, v17, v17
	v_mul_f32_e32 v47, v19, v19
	v_mul_f32_e32 v54, v1, v1
	v_mul_f32_e32 v55, v3, v3
	v_add_f32_e32 v42, v44, v45
	v_fmac_f32_e32 v52, v4, v4
	v_fmac_f32_e32 v53, v6, v6
	v_add_f32_e32 v40, v40, v41
	v_add_f32_e32 v41, v48, v49
	v_add_f32_e32 v44, v50, v51
	v_fmac_f32_e32 v46, v16, v16
	v_fmac_f32_e32 v47, v18, v18
	v_fmac_f32_e32 v54, v0, v0
	v_fmac_f32_e32 v55, v2, v2
	v_add_f32_e32 v45, v52, v53
	v_add_f32_e32 v41, v41, v44
	v_add_f32_e32 v43, v46, v47
	v_add_f32_e32 v46, v54, v55
	v_add_f32_e32 v40, v40, v42
	v_add_f32_e32 v41, v41, v45
	v_add_f32_e32 v40, v40, v43
	v_add_f32_e32 v41, v41, v46
	ds_swizzle_b32 v42, v40 offset:swizzle(SWAP,1)
	ds_swizzle_b32 v43, v41 offset:swizzle(SWAP,1)
	s_waitcnt lgkmcnt(1)
	v_add_f32_e32 v40, v40, v42
	s_waitcnt lgkmcnt(0)
	v_add_f32_e32 v41, v41, v43
	ds_swizzle_b32 v42, v40 offset:swizzle(SWAP,2)
	ds_swizzle_b32 v43, v41 offset:swizzle(SWAP,2)
	s_waitcnt lgkmcnt(1)
	v_add_f32_e32 v40, v40, v42
	s_waitcnt lgkmcnt(0)
	v_add_f32_e32 v41, v41, v43
	ds_swizzle_b32 v42, v40 offset:swizzle(SWAP,4)
	ds_swizzle_b32 v43, v41 offset:swizzle(SWAP,4)
	s_waitcnt lgkmcnt(1)
	v_add_f32_e32 v40, v40, v42
	s_waitcnt lgkmcnt(0)
	v_add_f32_e32 v41, v41, v43
	ds_swizzle_b32 v42, v40 offset:swizzle(SWAP,8)
	ds_swizzle_b32 v43, v41 offset:swizzle(SWAP,8)
	s_waitcnt lgkmcnt(1)
	v_add_f32_e32 v40, v40, v42
	s_waitcnt lgkmcnt(0)
	v_add_f32_e32 v41, v41, v43
	ds_swizzle_b32 v42, v40 offset:swizzle(SWAP,16)
	ds_swizzle_b32 v43, v41 offset:swizzle(SWAP,16)
	s_waitcnt lgkmcnt(1)
	v_add_f32_e32 v42, v40, v42
	s_waitcnt lgkmcnt(0)
	v_add_f32_e32 v40, v41, v43
	v_mov_b32_e32 v43, v42
	v_mov_b32_e32 v41, v40
	s_nop 0
	v_permlane32_swap_b32_e32 v42, v43
	v_permlane32_swap_b32_e32 v40, v41
	v_add_f32_e32 v42, v42, v43
	v_add_f32_e32 v40, v40, v41
	s_ashr_i32 s11, s10, 31
	s_lshl_b64 s[12:13], s[10:11], 2
	s_add_u32 s12, s3, s12
	s_addc_u32 s13, s9, s13
	s_mov_b32 s14, s0
	s_ashr_i32 s15, s0, 31
	s_lshl_b64 s[14:15], s[14:15], 2
	s_add_u32 s14, s3, s14
	s_addc_u32 s15, s9, s15
	s_and_saveexec_b64 s[16:17], vcc
	global_store_dword v177, v42, s[12:13]
	global_store_dword v177, v40, s[14:15]
	s_or_b64 exec, exec, s[16:17]
	s_lshl_b64 s[12:13], s[10:11], 11
	v_lshl_add_u64 v[140:141], v[34:35], 0, s[12:13]
	s_mov_b32 s14, s0
	s_ashr_i32 s15, s0, 31
	s_lshl_b64 s[14:15], s[14:15], 11
	v_lshl_add_u64 v[142:143], v[34:35], 0, s[14:15]
	s_cmpk_gt_i32 s1, 0x7fff
	s_cbranch_scc1 .Lprep_w2
	s_waitcnt vmcnt(10)
	s_branch .Lprep_w
; __device__ __forceinline__ unsigned pk2(float lo, float hi) { unsigned r; asm volatile("v_cvt_pk_bf16_f32 %0, %1, %2" : "=v"(r) : "v"(lo), "v"(hi)); return r; }
; __device__ __forceinline__ void prep_phase(const PL& P, int gw, int NGW, int lane) {
;     ...
;           for (int k = 0; k < 2; ++k) { const int row = row0 + k * NGW; const int b = row >> 13; if (lane == 0) ssq0[row] = ss[k];
;               v2u* ao = (v2u*)(a + (size_t)row * D) + lane;
; #pragma unroll
;               for (int j = 0; j < 4; ++j) { const f32x4 gg = *((const f32x4*)g + lane + 64 * j), c4 = *((const f32x4*)(sc + (size_t)b * NMOD) + lane + 64 * j);
;                   const f32x4 y = v[k][j] * gg * (c4 + 1.0f); v2u w; w.x = pk2(y.x, y.y); w.y = pk2(y.z, y.w); ao[64 * j] = w; } } } }
.Lprep_w2:
	s_waitcnt vmcnt(2)
.Lprep_w:
	v_pk_mul_f32 v[30:31], v[30:31], v[58:59]
	v_pk_mul_f32 v[28:29], v[28:29], v[56:57]
	v_pk_add_f32 v[104:105], v[104:105], 1.0 op_sel_hi:[1,0]
	v_pk_add_f32 v[106:107], v[106:107], 1.0 op_sel_hi:[1,0]
	v_pk_mul_f32 v[28:29], v[28:29], v[104:105]
	v_pk_mul_f32 v[30:31], v[30:31], v[106:107]
	v_cvt_pk_bf16_f32 v28, v28, v29
	v_cvt_pk_bf16_f32 v29, v30, v31
	global_store_dwordx2 v[140:141], v[28:29], off
	v_pk_mul_f32 v[26:27], v[26:27], v[62:63]
	v_pk_mul_f32 v[24:25], v[24:25], v[60:61]
	v_pk_add_f32 v[108:109], v[108:109], 1.0 op_sel_hi:[1,0]
	v_pk_add_f32 v[110:111], v[110:111], 1.0 op_sel_hi:[1,0]
	v_pk_mul_f32 v[24:25], v[24:25], v[108:109]
	v_pk_mul_f32 v[26:27], v[26:27], v[110:111]
	v_cvt_pk_bf16_f32 v24, v24, v25
	v_cvt_pk_bf16_f32 v25, v26, v27
	global_store_dwordx2 v[140:141], v[24:25], off offset:512
	v_pk_mul_f32 v[22:23], v[22:23], v[66:67]
	v_pk_mul_f32 v[20:21], v[20:21], v[64:65]
	v_pk_add_f32 v[112:113], v[112:113], 1.0 op_sel_hi:[1,0]
	v_pk_add_f32 v[114:115], v[114:115], 1.0 op_sel_hi:[1,0]
	v_pk_mul_f32 v[20:21], v[20:21], v[112:113]
	v_pk_mul_f32 v[22:23], v[22:23], v[114:115]
	v_cvt_pk_bf16_f32 v20, v20, v21
	v_cvt_pk_bf16_f32 v21, v22, v23
	global_store_dwordx2 v[140:141], v[20:21], off offset:1024
	v_pk_mul_f32 v[18:19], v[18:19], v[70:71]
	v_pk_mul_f32 v[16:17], v[16:17], v[68:69]
	v_pk_add_f32 v[116:117], v[116:117], 1.0 op_sel_hi:[1,0]
	v_pk_add_f32 v[118:119], v[118:119], 1.0 op_sel_hi:[1,0]
	v_pk_mul_f32 v[16:17], v[16:17], v[116:117]
	v_pk_mul_f32 v[18:19], v[18:19], v[118:119]
	v_cvt_pk_bf16_f32 v16, v16, v17
	v_cvt_pk_bf16_f32 v17, v18, v19
	global_store_dwordx2 v[140:141], v[16:17], off offset:1536
	v_pk_mul_f32 v[14:15], v[14:15], v[58:59]
	v_pk_mul_f32 v[12:13], v[12:13], v[56:57]
	v_pk_add_f32 v[120:121], v[120:121], 1.0 op_sel_hi:[1,0]
	v_pk_add_f32 v[122:123], v[122:123], 1.0 op_sel_hi:[1,0]
	v_pk_mul_f32 v[12:13], v[12:13], v[120:121]
	v_pk_mul_f32 v[14:15], v[14:15], v[122:123]
	v_cvt_pk_bf16_f32 v12, v12, v13
	v_cvt_pk_bf16_f32 v13, v14, v15
	global_store_dwordx2 v[142:143], v[12:13], off
	v_pk_mul_f32 v[10:11], v[10:11], v[62:63]
	v_pk_mul_f32 v[8:9], v[8:9], v[60:61]
	v_pk_add_f32 v[124:125], v[124:125], 1.0 op_sel_hi:[1,0]
	v_pk_add_f32 v[126:127], v[126:127], 1.0 op_sel_hi:[1,0]
	v_pk_mul_f32 v[8:9], v[8:9], v[124:125]
	v_pk_mul_f32 v[10:11], v[10:11], v[126:127]
	v_cvt_pk_bf16_f32 v8, v8, v9
	v_cvt_pk_bf16_f32 v9, v10, v11
	global_store_dwordx2 v[142:143], v[8:9], off offset:512
	v_pk_mul_f32 v[6:7], v[6:7], v[66:67]
	v_pk_mul_f32 v[4:5], v[4:5], v[64:65]
	v_pk_add_f32 v[128:129], v[128:129], 1.0 op_sel_hi:[1,0]
	v_pk_add_f32 v[130:131], v[130:131], 1.0 op_sel_hi:[1,0]
	v_pk_mul_f32 v[4:5], v[4:5], v[128:129]
	v_pk_mul_f32 v[6:7], v[6:7], v[130:131]
	v_cvt_pk_bf16_f32 v4, v4, v5
	v_cvt_pk_bf16_f32 v5, v6, v7
	global_store_dwordx2 v[142:143], v[4:5], off offset:1024
	v_pk_mul_f32 v[2:3], v[2:3], v[70:71]
	v_pk_mul_f32 v[0:1], v[0:1], v[68:69]
	v_pk_add_f32 v[132:133], v[132:133], 1.0 op_sel_hi:[1,0]
	v_pk_add_f32 v[134:135], v[134:135], 1.0 op_sel_hi:[1,0]
	v_pk_mul_f32 v[0:1], v[0:1], v[132:133]
	v_pk_mul_f32 v[2:3], v[2:3], v[134:135]
	v_cvt_pk_bf16_f32 v0, v0, v1
	v_cvt_pk_bf16_f32 v1, v2, v3
	global_store_dwordx2 v[142:143], v[0:1], off offset:1536
	s_cmpk_gt_i32 s1, 0x7fff
	s_cbranch_scc1 .LBB0_577
	s_ashr_i32 s12, s1, 13
	v_mad_i64_i32 v[138:139], s[12:13], s12, v226, v[38:39]
	global_load_dwordx4 v[104:107], v[138:139], off
	global_load_dwordx4 v[108:111], v[138:139], off offset:1024
	global_load_dwordx4 v[112:115], v[138:139], off offset:2048
	global_load_dwordx4 v[116:119], v[138:139], off offset:3072
	s_add_i32 s12, s1, s2
	s_ashr_i32 s12, s12, 13
	v_mad_i64_i32 v[138:139], s[12:13], s12, v226, v[38:39]
	global_load_dwordx4 v[120:123], v[138:139], off
	global_load_dwordx4 v[124:127], v[138:139], off offset:1024
	global_load_dwordx4 v[128:131], v[138:139], off offset:2048
	global_load_dwordx4 v[132:135], v[138:139], off offset:3072
	s_mov_b32 s10, s1
	s_waitcnt vmcnt(18)
	s_branch .Lprep_loop
